# generic bf16 epilogue (G1 kinds 0,1,2,5,6,7) with lane-transposed stores too; on top of v50
# baseline (speedup 1.0000x reference)
; __device__ __forceinline__ u32x2 pack4(f32x4 v) { u32x2 r; r[0] = cvt_pk(v[0], v[1]); r[1] = cvt_pk(v[2], v[3]); return r; }
; __device__ __forceinline__ float sigmoidf_(float x) { return __builtin_amdgcn_rcpf(1.0f + __expf(-x)); }
; __device__ __forceinline__ float gelu_tanh(float x) { const float z = 1.5957691216057308f * (x + 0.044715f * x * x * x); return x * sigmoidf_(z); }
; __device__ __forceinline__ float siluf_(float x) { return x * sigmoidf_(x); }
; __device__ __forceinline__ void epilogue(const Params& p, const Unit& u, const f32x4 (&acc)[2][2][4][2], int wr, int wc, int fr, int fq) {
;     ...
; #pragma unroll
;     for (int ai = 0; ai < 2; ++ai)
; #pragma unroll
;       for (int m = 0; m < 4; ++m) {
;         bf16_t* rp = dst + (size_t)(row0 + ai * 128 + m * 16) * ld + cb + ct0;
; #pragma unroll
;         for (int bj = 0; bj < 2; ++bj)
; #pragma unroll
;           for (int n = 0; n < 2; ++n) {
;             f32x4 v = acc[ai][bj][m][n];
;             if (act == 1) { v[0] = sigmoidf_(v[0]); v[1] = sigmoidf_(v[1]); v[2] = sigmoidf_(v[2]); v[3] = sigmoidf_(v[3]); }
;             else if (act == 2) { v[0] = gelu_tanh(v[0]); v[1] = gelu_tanh(v[1]); v[2] = gelu_tanh(v[2]); v[3] = gelu_tanh(v[3]); }
;             else if (act == 3) { v[0] = siluf_(v[0]); v[1] = siluf_(v[1]); v[2] = siluf_(v[2]); v[3] = siluf_(v[3]); }
;             else { v = v * scale; }
;             *(u32x2*)(rp + bj * 128 + n * 16) = pack4(v);
;           }
.LBB0_401:
	s_ashr_i32 s39, s38, 31
	s_lshl_b64 s[34:35], s[38:39], 1
	s_add_u32 s34, s66, s34
	s_addc_u32 s35, s67, s35
	v_lshrrev_b32_e32 v141, 2, v230
	v_and_b32_e32 v142, 3, v230
	v_lshlrev_b32_e32 v140, 6, v142
	v_lshl_add_u32 v140, v141, 2, v140
	v_and_b32_e32 v66, -16, v66
	v_or_b32_e32 v66, v66, v141
	v_and_b32_e32 v64, 0x60, v174
	v_lshl_add_u32 v64, v142, 2, v64
	v_lshlrev_b32_e32 v64, 1, v64
	v_lshl_add_u64 v[132:133], s[34:35], 0, v[64:65]
	v_cndmask_b32_e64 v64, 0, 1, s[36:37]
	v_mad_i64_i32 v[134:135], s[34:35], s64, v66, 0
	v_cmp_ne_u32_e64 s[38:39], 1, v64
	v_cndmask_b32_e64 v64, 0, 1, s[68:69]
	v_lshl_add_u64 v[134:135], v[134:135], 1, v[132:133]
	v_cvt_pk_bf16_f32 v138, v138, v139
	v_cvt_pk_bf16_f32 v139, v136, v137
	s_andn2_b64 vcc, exec, s[36:37]
	v_cmp_ne_u32_e64 s[36:37], 1, v64
	ds_bpermute_b32 v138, v140, v138
	ds_bpermute_b32 v139, v140, v139
	s_waitcnt lgkmcnt(0)
	global_store_dwordx2 v[134:135], v[138:139], off
	s_cbranch_vccnz .LBB0_743
	s_and_b64 vcc, exec, s[36:37]
	s_mov_b64 s[66:67], -1
	s_cbranch_vccnz .LBB0_408
	s_andn2_b64 vcc, exec, s[62:63]
	s_cbranch_vccnz .LBB0_405
	s_mov_b32 s34, s40
	s_mov_b32 s35, s40
	v_pk_mul_f32 v[136:137], v[126:127], s[34:35]
	v_pk_mul_f32 v[138:139], v[124:125], s[40:41]
	s_mov_b64 s[66:67], 0

; __device__ __forceinline__ u32x2 pack4(f32x4 v) { u32x2 r; r[0] = cvt_pk(v[0], v[1]); r[1] = cvt_pk(v[2], v[3]); return r; }
; __device__ __forceinline__ float sigmoidf_(float x) { return __builtin_amdgcn_rcpf(1.0f + __expf(-x)); }
; __device__ __forceinline__ float gelu_tanh(float x) { const float z = 1.5957691216057308f * (x + 0.044715f * x * x * x); return x * sigmoidf_(z); }
; __device__ __forceinline__ float siluf_(float x) { return x * sigmoidf_(x); }
; __device__ __forceinline__ void epilogue(const Params& p, const Unit& u, const f32x4 (&acc)[2][2][4][2], int wr, int wc, int fr, int fq) {
;     ...
; #pragma unroll
;     for (int ai = 0; ai < 2; ++ai)
; #pragma unroll
;       for (int m = 0; m < 4; ++m) {
;         bf16_t* rp = dst + (size_t)(row0 + ai * 128 + m * 16) * ld + cb + ct0;
; #pragma unroll
;         for (int bj = 0; bj < 2; ++bj)
; #pragma unroll
;           for (int n = 0; n < 2; ++n) {
;             f32x4 v = acc[ai][bj][m][n];
;             if (act == 1) { v[0] = sigmoidf_(v[0]); v[1] = sigmoidf_(v[1]); v[2] = sigmoidf_(v[2]); v[3] = sigmoidf_(v[3]); }
;             else if (act == 2) { v[0] = gelu_tanh(v[0]); v[1] = gelu_tanh(v[1]); v[2] = gelu_tanh(v[2]); v[3] = gelu_tanh(v[3]); }
;             else if (act == 3) { v[0] = siluf_(v[0]); v[1] = siluf_(v[1]); v[2] = siluf_(v[2]); v[3] = siluf_(v[3]); }
;             else { v = v * scale; }
;             *(u32x2*)(rp + bj * 128 + n * 16) = pack4(v);
;           }
.LBB0_412:
	v_cvt_pk_bf16_f32 v138, v138, v139
	v_cvt_pk_bf16_f32 v139, v136, v137
	s_and_b64 vcc, exec, s[38:39]
	ds_bpermute_b32 v138, v140, v138
	ds_bpermute_b32 v139, v140, v139
	s_waitcnt lgkmcnt(0)
	global_store_dwordx2 v[134:135], v[138:139], off offset:32
	s_cbranch_vccnz .LBB0_744
	s_and_b64 vcc, exec, s[36:37]
	s_mov_b64 s[66:67], -1
	s_cbranch_vccnz .LBB0_419
	s_andn2_b64 vcc, exec, s[62:63]
	s_cbranch_vccnz .LBB0_416
	s_mov_b32 s34, s40
	s_mov_b32 s35, s40
	v_pk_mul_f32 v[136:137], v[98:99], s[34:35]
	v_pk_mul_f32 v[138:139], v[96:97], s[40:41]
	s_mov_b64 s[66:67], 0

; __device__ __forceinline__ u32x2 pack4(f32x4 v) { u32x2 r; r[0] = cvt_pk(v[0], v[1]); r[1] = cvt_pk(v[2], v[3]); return r; }
; __device__ __forceinline__ float sigmoidf_(float x) { return __builtin_amdgcn_rcpf(1.0f + __expf(-x)); }
; __device__ __forceinline__ float gelu_tanh(float x) { const float z = 1.5957691216057308f * (x + 0.044715f * x * x * x); return x * sigmoidf_(z); }
; __device__ __forceinline__ float siluf_(float x) { return x * sigmoidf_(x); }
; __device__ __forceinline__ void epilogue(const Params& p, const Unit& u, const f32x4 (&acc)[2][2][4][2], int wr, int wc, int fr, int fq) {
;     ...
; #pragma unroll
;     for (int ai = 0; ai < 2; ++ai)
; #pragma unroll
;       for (int m = 0; m < 4; ++m) {
;         bf16_t* rp = dst + (size_t)(row0 + ai * 128 + m * 16) * ld + cb + ct0;
; #pragma unroll
;         for (int bj = 0; bj < 2; ++bj)
; #pragma unroll
;           for (int n = 0; n < 2; ++n) {
;             f32x4 v = acc[ai][bj][m][n];
;             if (act == 1) { v[0] = sigmoidf_(v[0]); v[1] = sigmoidf_(v[1]); v[2] = sigmoidf_(v[2]); v[3] = sigmoidf_(v[3]); }
;             else if (act == 2) { v[0] = gelu_tanh(v[0]); v[1] = gelu_tanh(v[1]); v[2] = gelu_tanh(v[2]); v[3] = gelu_tanh(v[3]); }
;             else if (act == 3) { v[0] = siluf_(v[0]); v[1] = siluf_(v[1]); v[2] = siluf_(v[2]); v[3] = siluf_(v[3]); }
;             else { v = v * scale; }
;             *(u32x2*)(rp + bj * 128 + n * 16) = pack4(v);
;           }
.LBB0_423:
	v_cvt_pk_bf16_f32 v138, v138, v139
	v_cvt_pk_bf16_f32 v139, v136, v137
	s_and_b64 vcc, exec, s[38:39]
	ds_bpermute_b32 v138, v140, v138
	ds_bpermute_b32 v139, v140, v139
	s_waitcnt lgkmcnt(0)
	global_store_dwordx2 v[134:135], v[138:139], off offset:256
	s_cbranch_vccnz .LBB0_745
	s_and_b64 vcc, exec, s[36:37]
	s_mov_b64 s[66:67], -1
	s_cbranch_vccnz .LBB0_430
	s_andn2_b64 vcc, exec, s[62:63]
	s_cbranch_vccnz .LBB0_427
	s_mov_b32 s34, s40
	s_mov_b32 s35, s40
	v_pk_mul_f32 v[136:137], v[94:95], s[34:35]
	v_pk_mul_f32 v[138:139], v[92:93], s[40:41]
	s_mov_b64 s[66:67], 0

; __device__ __forceinline__ u32x2 pack4(f32x4 v) { u32x2 r; r[0] = cvt_pk(v[0], v[1]); r[1] = cvt_pk(v[2], v[3]); return r; }
; __device__ __forceinline__ float sigmoidf_(float x) { return __builtin_amdgcn_rcpf(1.0f + __expf(-x)); }
; __device__ __forceinline__ float gelu_tanh(float x) { const float z = 1.5957691216057308f * (x + 0.044715f * x * x * x); return x * sigmoidf_(z); }
; __device__ __forceinline__ float siluf_(float x) { return x * sigmoidf_(x); }
; __device__ __forceinline__ void epilogue(const Params& p, const Unit& u, const f32x4 (&acc)[2][2][4][2], int wr, int wc, int fr, int fq) {
;     ...
; #pragma unroll
;     for (int ai = 0; ai < 2; ++ai)
; #pragma unroll
;       for (int m = 0; m < 4; ++m) {
;         bf16_t* rp = dst + (size_t)(row0 + ai * 128 + m * 16) * ld + cb + ct0;
; #pragma unroll
;         for (int bj = 0; bj < 2; ++bj)
; #pragma unroll
;           for (int n = 0; n < 2; ++n) {
;             f32x4 v = acc[ai][bj][m][n];
;             if (act == 1) { v[0] = sigmoidf_(v[0]); v[1] = sigmoidf_(v[1]); v[2] = sigmoidf_(v[2]); v[3] = sigmoidf_(v[3]); }
;             else if (act == 2) { v[0] = gelu_tanh(v[0]); v[1] = gelu_tanh(v[1]); v[2] = gelu_tanh(v[2]); v[3] = gelu_tanh(v[3]); }
;             else if (act == 3) { v[0] = siluf_(v[0]); v[1] = siluf_(v[1]); v[2] = siluf_(v[2]); v[3] = siluf_(v[3]); }
;             else { v = v * scale; }
;             *(u32x2*)(rp + bj * 128 + n * 16) = pack4(v);
;           }
.LBB0_434:
	v_cvt_pk_bf16_f32 v138, v138, v139
	v_cvt_pk_bf16_f32 v139, v136, v137
	s_and_b64 vcc, exec, s[38:39]
	ds_bpermute_b32 v138, v140, v138
	ds_bpermute_b32 v139, v140, v139
	s_waitcnt lgkmcnt(0)
	global_store_dwordx2 v[134:135], v[138:139], off offset:288
	s_cbranch_vccnz .LBB0_746
	s_and_b64 vcc, exec, s[36:37]
	s_mov_b64 s[66:67], -1
	s_cbranch_vccnz .LBB0_441
	s_andn2_b64 vcc, exec, s[62:63]
	s_cbranch_vccnz .LBB0_438
	s_mov_b32 s34, s40
	s_mov_b32 s35, s40
	v_pk_mul_f32 v[136:137], v[122:123], s[34:35]
	v_pk_mul_f32 v[138:139], v[120:121], s[40:41]
	s_mov_b64 s[66:67], 0

; __device__ __forceinline__ u32x2 pack4(f32x4 v) { u32x2 r; r[0] = cvt_pk(v[0], v[1]); r[1] = cvt_pk(v[2], v[3]); return r; }
; __device__ __forceinline__ float sigmoidf_(float x) { return __builtin_amdgcn_rcpf(1.0f + __expf(-x)); }
; __device__ __forceinline__ float gelu_tanh(float x) { const float z = 1.5957691216057308f * (x + 0.044715f * x * x * x); return x * sigmoidf_(z); }
; __device__ __forceinline__ float siluf_(float x) { return x * sigmoidf_(x); }
; __device__ __forceinline__ void epilogue(const Params& p, const Unit& u, const f32x4 (&acc)[2][2][4][2], int wr, int wc, int fr, int fq) {
;     ...
; #pragma unroll
;     for (int ai = 0; ai < 2; ++ai)
; #pragma unroll
;       for (int m = 0; m < 4; ++m) {
;         bf16_t* rp = dst + (size_t)(row0 + ai * 128 + m * 16) * ld + cb + ct0;
; #pragma unroll
;         for (int bj = 0; bj < 2; ++bj)
; #pragma unroll
;           for (int n = 0; n < 2; ++n) {
;             f32x4 v = acc[ai][bj][m][n];
;             if (act == 1) { v[0] = sigmoidf_(v[0]); v[1] = sigmoidf_(v[1]); v[2] = sigmoidf_(v[2]); v[3] = sigmoidf_(v[3]); }
;             else if (act == 2) { v[0] = gelu_tanh(v[0]); v[1] = gelu_tanh(v[1]); v[2] = gelu_tanh(v[2]); v[3] = gelu_tanh(v[3]); }
;             else if (act == 3) { v[0] = siluf_(v[0]); v[1] = siluf_(v[1]); v[2] = siluf_(v[2]); v[3] = siluf_(v[3]); }
;             else { v = v * scale; }
;             *(u32x2*)(rp + bj * 128 + n * 16) = pack4(v);
;           }
.LBB0_445:
	v_or_b32_e32 v64, 16, v66
	v_mad_i64_i32 v[134:135], s[34:35], s64, v64, 0
	v_lshl_add_u64 v[134:135], v[134:135], 1, v[132:133]
	v_cvt_pk_bf16_f32 v138, v138, v139
	v_cvt_pk_bf16_f32 v139, v136, v137
	s_and_b64 vcc, exec, s[38:39]
	ds_bpermute_b32 v138, v140, v138
	ds_bpermute_b32 v139, v140, v139
	s_waitcnt lgkmcnt(0)
	global_store_dwordx2 v[134:135], v[138:139], off
	s_cbranch_vccnz .LBB0_747
	s_and_b64 vcc, exec, s[36:37]
	s_mov_b64 s[66:67], -1
	s_cbranch_vccnz .LBB0_452
	s_andn2_b64 vcc, exec, s[62:63]
	s_cbranch_vccnz .LBB0_449
	s_mov_b32 s34, s40
	s_mov_b32 s35, s40
	v_pk_mul_f32 v[136:137], v[118:119], s[34:35]
	v_pk_mul_f32 v[138:139], v[116:117], s[40:41]
	s_mov_b64 s[66:67], 0

; __device__ __forceinline__ u32x2 pack4(f32x4 v) { u32x2 r; r[0] = cvt_pk(v[0], v[1]); r[1] = cvt_pk(v[2], v[3]); return r; }
; __device__ __forceinline__ float sigmoidf_(float x) { return __builtin_amdgcn_rcpf(1.0f + __expf(-x)); }
; __device__ __forceinline__ float gelu_tanh(float x) { const float z = 1.5957691216057308f * (x + 0.044715f * x * x * x); return x * sigmoidf_(z); }
; __device__ __forceinline__ float siluf_(float x) { return x * sigmoidf_(x); }
; __device__ __forceinline__ void epilogue(const Params& p, const Unit& u, const f32x4 (&acc)[2][2][4][2], int wr, int wc, int fr, int fq) {
;     ...
; #pragma unroll
;     for (int ai = 0; ai < 2; ++ai)
; #pragma unroll
;       for (int m = 0; m < 4; ++m) {
;         bf16_t* rp = dst + (size_t)(row0 + ai * 128 + m * 16) * ld + cb + ct0;
; #pragma unroll
;         for (int bj = 0; bj < 2; ++bj)
; #pragma unroll
;           for (int n = 0; n < 2; ++n) {
;             f32x4 v = acc[ai][bj][m][n];
;             if (act == 1) { v[0] = sigmoidf_(v[0]); v[1] = sigmoidf_(v[1]); v[2] = sigmoidf_(v[2]); v[3] = sigmoidf_(v[3]); }
;             else if (act == 2) { v[0] = gelu_tanh(v[0]); v[1] = gelu_tanh(v[1]); v[2] = gelu_tanh(v[2]); v[3] = gelu_tanh(v[3]); }
;             else if (act == 3) { v[0] = siluf_(v[0]); v[1] = siluf_(v[1]); v[2] = siluf_(v[2]); v[3] = siluf_(v[3]); }
;             else { v = v * scale; }
;             *(u32x2*)(rp + bj * 128 + n * 16) = pack4(v);
;           }
.LBB0_456:
	v_cvt_pk_bf16_f32 v138, v138, v139
	v_cvt_pk_bf16_f32 v139, v136, v137
	s_and_b64 vcc, exec, s[38:39]
	ds_bpermute_b32 v138, v140, v138
	ds_bpermute_b32 v139, v140, v139
	s_waitcnt lgkmcnt(0)
	global_store_dwordx2 v[134:135], v[138:139], off offset:32
	s_cbranch_vccnz .LBB0_748
	s_and_b64 vcc, exec, s[36:37]
	s_mov_b64 s[66:67], -1
	s_cbranch_vccnz .LBB0_463
	s_andn2_b64 vcc, exec, s[62:63]
	s_cbranch_vccnz .LBB0_460
	s_mov_b32 s34, s40
	s_mov_b32 s35, s40
	v_pk_mul_f32 v[136:137], v[90:91], s[34:35]
	v_pk_mul_f32 v[138:139], v[88:89], s[40:41]
	s_mov_b64 s[66:67], 0

; __device__ __forceinline__ u32x2 pack4(f32x4 v) { u32x2 r; r[0] = cvt_pk(v[0], v[1]); r[1] = cvt_pk(v[2], v[3]); return r; }
; __device__ __forceinline__ float sigmoidf_(float x) { return __builtin_amdgcn_rcpf(1.0f + __expf(-x)); }
; __device__ __forceinline__ float gelu_tanh(float x) { const float z = 1.5957691216057308f * (x + 0.044715f * x * x * x); return x * sigmoidf_(z); }
; __device__ __forceinline__ float siluf_(float x) { return x * sigmoidf_(x); }
; __device__ __forceinline__ void epilogue(const Params& p, const Unit& u, const f32x4 (&acc)[2][2][4][2], int wr, int wc, int fr, int fq) {
;     ...
; #pragma unroll
;     for (int ai = 0; ai < 2; ++ai)
; #pragma unroll
;       for (int m = 0; m < 4; ++m) {
;         bf16_t* rp = dst + (size_t)(row0 + ai * 128 + m * 16) * ld + cb + ct0;
; #pragma unroll
;         for (int bj = 0; bj < 2; ++bj)
; #pragma unroll
;           for (int n = 0; n < 2; ++n) {
;             f32x4 v = acc[ai][bj][m][n];
;             if (act == 1) { v[0] = sigmoidf_(v[0]); v[1] = sigmoidf_(v[1]); v[2] = sigmoidf_(v[2]); v[3] = sigmoidf_(v[3]); }
;             else if (act == 2) { v[0] = gelu_tanh(v[0]); v[1] = gelu_tanh(v[1]); v[2] = gelu_tanh(v[2]); v[3] = gelu_tanh(v[3]); }
;             else if (act == 3) { v[0] = siluf_(v[0]); v[1] = siluf_(v[1]); v[2] = siluf_(v[2]); v[3] = siluf_(v[3]); }
;             else { v = v * scale; }
;             *(u32x2*)(rp + bj * 128 + n * 16) = pack4(v);
;           }
.LBB0_467:
	v_cvt_pk_bf16_f32 v138, v138, v139
	v_cvt_pk_bf16_f32 v139, v136, v137
	s_and_b64 vcc, exec, s[38:39]
	ds_bpermute_b32 v138, v140, v138
	ds_bpermute_b32 v139, v140, v139
	s_waitcnt lgkmcnt(0)
	global_store_dwordx2 v[134:135], v[138:139], off offset:256
	s_cbranch_vccnz .LBB0_749
	s_and_b64 vcc, exec, s[36:37]
	s_mov_b64 s[66:67], -1
	s_cbranch_vccnz .LBB0_474
	s_andn2_b64 vcc, exec, s[62:63]
	s_cbranch_vccnz .LBB0_471
	s_mov_b32 s34, s40
	s_mov_b32 s35, s40
	v_pk_mul_f32 v[136:137], v[86:87], s[34:35]
	v_pk_mul_f32 v[138:139], v[84:85], s[40:41]
	s_mov_b64 s[66:67], 0

; __device__ __forceinline__ u32x2 pack4(f32x4 v) { u32x2 r; r[0] = cvt_pk(v[0], v[1]); r[1] = cvt_pk(v[2], v[3]); return r; }
; __device__ __forceinline__ float sigmoidf_(float x) { return __builtin_amdgcn_rcpf(1.0f + __expf(-x)); }
; __device__ __forceinline__ float gelu_tanh(float x) { const float z = 1.5957691216057308f * (x + 0.044715f * x * x * x); return x * sigmoidf_(z); }
; __device__ __forceinline__ float siluf_(float x) { return x * sigmoidf_(x); }
; __device__ __forceinline__ void epilogue(const Params& p, const Unit& u, const f32x4 (&acc)[2][2][4][2], int wr, int wc, int fr, int fq) {
;     ...
; #pragma unroll
;     for (int ai = 0; ai < 2; ++ai)
; #pragma unroll
;       for (int m = 0; m < 4; ++m) {
;         bf16_t* rp = dst + (size_t)(row0 + ai * 128 + m * 16) * ld + cb + ct0;
; #pragma unroll
;         for (int bj = 0; bj < 2; ++bj)
; #pragma unroll
;           for (int n = 0; n < 2; ++n) {
;             f32x4 v = acc[ai][bj][m][n];
;             if (act == 1) { v[0] = sigmoidf_(v[0]); v[1] = sigmoidf_(v[1]); v[2] = sigmoidf_(v[2]); v[3] = sigmoidf_(v[3]); }
;             else if (act == 2) { v[0] = gelu_tanh(v[0]); v[1] = gelu_tanh(v[1]); v[2] = gelu_tanh(v[2]); v[3] = gelu_tanh(v[3]); }
;             else if (act == 3) { v[0] = siluf_(v[0]); v[1] = siluf_(v[1]); v[2] = siluf_(v[2]); v[3] = siluf_(v[3]); }
;             else { v = v * scale; }
;             *(u32x2*)(rp + bj * 128 + n * 16) = pack4(v);
;           }
.LBB0_478:
	v_cvt_pk_bf16_f32 v138, v138, v139
	v_cvt_pk_bf16_f32 v139, v136, v137
	s_and_b64 vcc, exec, s[38:39]
	ds_bpermute_b32 v138, v140, v138
	ds_bpermute_b32 v139, v140, v139
	s_waitcnt lgkmcnt(0)
	global_store_dwordx2 v[134:135], v[138:139], off offset:288
	s_cbranch_vccnz .LBB0_750
	s_and_b64 vcc, exec, s[36:37]
	s_mov_b64 s[66:67], -1
	s_cbranch_vccnz .LBB0_485
	s_andn2_b64 vcc, exec, s[62:63]
	s_cbranch_vccnz .LBB0_482
	s_mov_b32 s34, s40
	s_mov_b32 s35, s40
	v_pk_mul_f32 v[136:137], v[114:115], s[34:35]
	v_pk_mul_f32 v[138:139], v[112:113], s[40:41]
	s_mov_b64 s[66:67], 0

; __device__ __forceinline__ u32x2 pack4(f32x4 v) { u32x2 r; r[0] = cvt_pk(v[0], v[1]); r[1] = cvt_pk(v[2], v[3]); return r; }
; __device__ __forceinline__ float sigmoidf_(float x) { return __builtin_amdgcn_rcpf(1.0f + __expf(-x)); }
; __device__ __forceinline__ float gelu_tanh(float x) { const float z = 1.5957691216057308f * (x + 0.044715f * x * x * x); return x * sigmoidf_(z); }
; __device__ __forceinline__ float siluf_(float x) { return x * sigmoidf_(x); }
; __device__ __forceinline__ void epilogue(const Params& p, const Unit& u, const f32x4 (&acc)[2][2][4][2], int wr, int wc, int fr, int fq) {
;     ...
; #pragma unroll
;     for (int ai = 0; ai < 2; ++ai)
; #pragma unroll
;       for (int m = 0; m < 4; ++m) {
;         bf16_t* rp = dst + (size_t)(row0 + ai * 128 + m * 16) * ld + cb + ct0;
; #pragma unroll
;         for (int bj = 0; bj < 2; ++bj)
; #pragma unroll
;           for (int n = 0; n < 2; ++n) {
;             f32x4 v = acc[ai][bj][m][n];
;             if (act == 1) { v[0] = sigmoidf_(v[0]); v[1] = sigmoidf_(v[1]); v[2] = sigmoidf_(v[2]); v[3] = sigmoidf_(v[3]); }
;             else if (act == 2) { v[0] = gelu_tanh(v[0]); v[1] = gelu_tanh(v[1]); v[2] = gelu_tanh(v[2]); v[3] = gelu_tanh(v[3]); }
;             else if (act == 3) { v[0] = siluf_(v[0]); v[1] = siluf_(v[1]); v[2] = siluf_(v[2]); v[3] = siluf_(v[3]); }
;             else { v = v * scale; }
;             *(u32x2*)(rp + bj * 128 + n * 16) = pack4(v);
;           }
.LBB0_489:
	v_or_b32_e32 v64, 32, v66
	v_mad_i64_i32 v[134:135], s[34:35], s64, v64, 0
	v_lshl_add_u64 v[134:135], v[134:135], 1, v[132:133]
	v_cvt_pk_bf16_f32 v138, v138, v139
	v_cvt_pk_bf16_f32 v139, v136, v137
	s_and_b64 vcc, exec, s[38:39]
	ds_bpermute_b32 v138, v140, v138
	ds_bpermute_b32 v139, v140, v139
	s_waitcnt lgkmcnt(0)
	global_store_dwordx2 v[134:135], v[138:139], off
	s_cbranch_vccnz .LBB0_751
	s_and_b64 vcc, exec, s[36:37]
	s_mov_b64 s[66:67], -1
	s_cbranch_vccnz .LBB0_496
	s_andn2_b64 vcc, exec, s[62:63]
	s_cbranch_vccnz .LBB0_493
	s_mov_b32 s34, s40
	s_mov_b32 s35, s40
	v_pk_mul_f32 v[136:137], v[110:111], s[34:35]
	v_pk_mul_f32 v[138:139], v[108:109], s[40:41]
	s_mov_b64 s[66:67], 0

; __device__ __forceinline__ u32x2 pack4(f32x4 v) { u32x2 r; r[0] = cvt_pk(v[0], v[1]); r[1] = cvt_pk(v[2], v[3]); return r; }
; __device__ __forceinline__ float sigmoidf_(float x) { return __builtin_amdgcn_rcpf(1.0f + __expf(-x)); }
; __device__ __forceinline__ float gelu_tanh(float x) { const float z = 1.5957691216057308f * (x + 0.044715f * x * x * x); return x * sigmoidf_(z); }
; __device__ __forceinline__ float siluf_(float x) { return x * sigmoidf_(x); }
; __device__ __forceinline__ void epilogue(const Params& p, const Unit& u, const f32x4 (&acc)[2][2][4][2], int wr, int wc, int fr, int fq) {
;     ...
; #pragma unroll
;     for (int ai = 0; ai < 2; ++ai)
; #pragma unroll
;       for (int m = 0; m < 4; ++m) {
;         bf16_t* rp = dst + (size_t)(row0 + ai * 128 + m * 16) * ld + cb + ct0;
; #pragma unroll
;         for (int bj = 0; bj < 2; ++bj)
; #pragma unroll
;           for (int n = 0; n < 2; ++n) {
;             f32x4 v = acc[ai][bj][m][n];
;             if (act == 1) { v[0] = sigmoidf_(v[0]); v[1] = sigmoidf_(v[1]); v[2] = sigmoidf_(v[2]); v[3] = sigmoidf_(v[3]); }
;             else if (act == 2) { v[0] = gelu_tanh(v[0]); v[1] = gelu_tanh(v[1]); v[2] = gelu_tanh(v[2]); v[3] = gelu_tanh(v[3]); }
;             else if (act == 3) { v[0] = siluf_(v[0]); v[1] = siluf_(v[1]); v[2] = siluf_(v[2]); v[3] = siluf_(v[3]); }
;             else { v = v * scale; }
;             *(u32x2*)(rp + bj * 128 + n * 16) = pack4(v);
;           }
.LBB0_500:
	v_cvt_pk_bf16_f32 v138, v138, v139
	v_cvt_pk_bf16_f32 v139, v136, v137
	s_and_b64 vcc, exec, s[38:39]
	ds_bpermute_b32 v138, v140, v138
	ds_bpermute_b32 v139, v140, v139
	s_waitcnt lgkmcnt(0)
	global_store_dwordx2 v[134:135], v[138:139], off offset:32
	s_cbranch_vccnz .LBB0_752
	s_and_b64 vcc, exec, s[36:37]
	s_mov_b64 s[66:67], -1
	s_cbranch_vccnz .LBB0_507
	s_andn2_b64 vcc, exec, s[62:63]
	s_cbranch_vccnz .LBB0_504
	s_mov_b32 s34, s40
	s_mov_b32 s35, s40
	v_pk_mul_f32 v[136:137], v[82:83], s[34:35]
	v_pk_mul_f32 v[138:139], v[80:81], s[40:41]
	s_mov_b64 s[66:67], 0

; __device__ __forceinline__ u32x2 pack4(f32x4 v) { u32x2 r; r[0] = cvt_pk(v[0], v[1]); r[1] = cvt_pk(v[2], v[3]); return r; }
; __device__ __forceinline__ float sigmoidf_(float x) { return __builtin_amdgcn_rcpf(1.0f + __expf(-x)); }
; __device__ __forceinline__ float gelu_tanh(float x) { const float z = 1.5957691216057308f * (x + 0.044715f * x * x * x); return x * sigmoidf_(z); }
; __device__ __forceinline__ float siluf_(float x) { return x * sigmoidf_(x); }
; __device__ __forceinline__ void epilogue(const Params& p, const Unit& u, const f32x4 (&acc)[2][2][4][2], int wr, int wc, int fr, int fq) {
;     ...
; #pragma unroll
;     for (int ai = 0; ai < 2; ++ai)
; #pragma unroll
;       for (int m = 0; m < 4; ++m) {
;         bf16_t* rp = dst + (size_t)(row0 + ai * 128 + m * 16) * ld + cb + ct0;
; #pragma unroll
;         for (int bj = 0; bj < 2; ++bj)
; #pragma unroll
;           for (int n = 0; n < 2; ++n) {
;             f32x4 v = acc[ai][bj][m][n];
;             if (act == 1) { v[0] = sigmoidf_(v[0]); v[1] = sigmoidf_(v[1]); v[2] = sigmoidf_(v[2]); v[3] = sigmoidf_(v[3]); }
;             else if (act == 2) { v[0] = gelu_tanh(v[0]); v[1] = gelu_tanh(v[1]); v[2] = gelu_tanh(v[2]); v[3] = gelu_tanh(v[3]); }
;             else if (act == 3) { v[0] = siluf_(v[0]); v[1] = siluf_(v[1]); v[2] = siluf_(v[2]); v[3] = siluf_(v[3]); }
;             else { v = v * scale; }
;             *(u32x2*)(rp + bj * 128 + n * 16) = pack4(v);
;           }
.LBB0_511:
	v_cvt_pk_bf16_f32 v138, v138, v139
	v_cvt_pk_bf16_f32 v139, v136, v137
	s_and_b64 vcc, exec, s[38:39]
	ds_bpermute_b32 v138, v140, v138
	ds_bpermute_b32 v139, v140, v139
	s_waitcnt lgkmcnt(0)
	global_store_dwordx2 v[134:135], v[138:139], off offset:256
	s_cbranch_vccnz .LBB0_753
	s_and_b64 vcc, exec, s[36:37]
	s_mov_b64 s[66:67], -1
	s_cbranch_vccnz .LBB0_518
	s_andn2_b64 vcc, exec, s[62:63]
	s_cbranch_vccnz .LBB0_515
	s_mov_b32 s34, s40
	s_mov_b32 s35, s40
	v_pk_mul_f32 v[136:137], v[78:79], s[34:35]
	v_pk_mul_f32 v[138:139], v[76:77], s[40:41]
	s_mov_b64 s[66:67], 0

; __device__ __forceinline__ u32x2 pack4(f32x4 v) { u32x2 r; r[0] = cvt_pk(v[0], v[1]); r[1] = cvt_pk(v[2], v[3]); return r; }
; __device__ __forceinline__ float sigmoidf_(float x) { return __builtin_amdgcn_rcpf(1.0f + __expf(-x)); }
; __device__ __forceinline__ float gelu_tanh(float x) { const float z = 1.5957691216057308f * (x + 0.044715f * x * x * x); return x * sigmoidf_(z); }
; __device__ __forceinline__ float siluf_(float x) { return x * sigmoidf_(x); }
; __device__ __forceinline__ void epilogue(const Params& p, const Unit& u, const f32x4 (&acc)[2][2][4][2], int wr, int wc, int fr, int fq) {
;     ...
; #pragma unroll
;     for (int ai = 0; ai < 2; ++ai)
; #pragma unroll
;       for (int m = 0; m < 4; ++m) {
;         bf16_t* rp = dst + (size_t)(row0 + ai * 128 + m * 16) * ld + cb + ct0;
; #pragma unroll
;         for (int bj = 0; bj < 2; ++bj)
; #pragma unroll
;           for (int n = 0; n < 2; ++n) {
;             f32x4 v = acc[ai][bj][m][n];
;             if (act == 1) { v[0] = sigmoidf_(v[0]); v[1] = sigmoidf_(v[1]); v[2] = sigmoidf_(v[2]); v[3] = sigmoidf_(v[3]); }
;             else if (act == 2) { v[0] = gelu_tanh(v[0]); v[1] = gelu_tanh(v[1]); v[2] = gelu_tanh(v[2]); v[3] = gelu_tanh(v[3]); }
;             else if (act == 3) { v[0] = siluf_(v[0]); v[1] = siluf_(v[1]); v[2] = siluf_(v[2]); v[3] = siluf_(v[3]); }
;             else { v = v * scale; }
;             *(u32x2*)(rp + bj * 128 + n * 16) = pack4(v);
;           }
.LBB0_522:
	v_cvt_pk_bf16_f32 v138, v138, v139
	v_cvt_pk_bf16_f32 v139, v136, v137
	s_and_b64 vcc, exec, s[38:39]
	ds_bpermute_b32 v138, v140, v138
	ds_bpermute_b32 v139, v140, v139
	s_waitcnt lgkmcnt(0)
	global_store_dwordx2 v[134:135], v[138:139], off offset:288
	s_cbranch_vccnz .LBB0_754
	s_and_b64 vcc, exec, s[36:37]
	s_mov_b64 s[66:67], -1
	s_cbranch_vccnz .LBB0_529
	s_andn2_b64 vcc, exec, s[62:63]
	s_cbranch_vccnz .LBB0_526
	s_mov_b32 s34, s40
	s_mov_b32 s35, s40
	v_pk_mul_f32 v[136:137], v[106:107], s[34:35]
	v_pk_mul_f32 v[138:139], v[104:105], s[40:41]
	s_mov_b64 s[66:67], 0

; __device__ __forceinline__ u32x2 pack4(f32x4 v) { u32x2 r; r[0] = cvt_pk(v[0], v[1]); r[1] = cvt_pk(v[2], v[3]); return r; }
; __device__ __forceinline__ float sigmoidf_(float x) { return __builtin_amdgcn_rcpf(1.0f + __expf(-x)); }
; __device__ __forceinline__ float gelu_tanh(float x) { const float z = 1.5957691216057308f * (x + 0.044715f * x * x * x); return x * sigmoidf_(z); }
; __device__ __forceinline__ float siluf_(float x) { return x * sigmoidf_(x); }
; __device__ __forceinline__ void epilogue(const Params& p, const Unit& u, const f32x4 (&acc)[2][2][4][2], int wr, int wc, int fr, int fq) {
;     ...
; #pragma unroll
;     for (int ai = 0; ai < 2; ++ai)
; #pragma unroll
;       for (int m = 0; m < 4; ++m) {
;         bf16_t* rp = dst + (size_t)(row0 + ai * 128 + m * 16) * ld + cb + ct0;
; #pragma unroll
;         for (int bj = 0; bj < 2; ++bj)
; #pragma unroll
;           for (int n = 0; n < 2; ++n) {
;             f32x4 v = acc[ai][bj][m][n];
;             if (act == 1) { v[0] = sigmoidf_(v[0]); v[1] = sigmoidf_(v[1]); v[2] = sigmoidf_(v[2]); v[3] = sigmoidf_(v[3]); }
;             else if (act == 2) { v[0] = gelu_tanh(v[0]); v[1] = gelu_tanh(v[1]); v[2] = gelu_tanh(v[2]); v[3] = gelu_tanh(v[3]); }
;             else if (act == 3) { v[0] = siluf_(v[0]); v[1] = siluf_(v[1]); v[2] = siluf_(v[2]); v[3] = siluf_(v[3]); }
;             else { v = v * scale; }
;             *(u32x2*)(rp + bj * 128 + n * 16) = pack4(v);
;           }
.LBB0_533:
	v_or_b32_e32 v64, 48, v66
	v_mad_i64_i32 v[134:135], s[34:35], s64, v64, 0
	v_lshl_add_u64 v[134:135], v[134:135], 1, v[132:133]
	v_cvt_pk_bf16_f32 v138, v138, v139
	v_cvt_pk_bf16_f32 v139, v136, v137
	s_and_b64 vcc, exec, s[38:39]
	ds_bpermute_b32 v138, v140, v138
	ds_bpermute_b32 v139, v140, v139
	s_waitcnt lgkmcnt(0)
	global_store_dwordx2 v[134:135], v[138:139], off
	s_cbranch_vccnz .LBB0_755
	s_and_b64 vcc, exec, s[36:37]
	s_mov_b64 s[66:67], -1
	s_cbranch_vccnz .LBB0_540
	s_andn2_b64 vcc, exec, s[62:63]
	s_cbranch_vccnz .LBB0_537
	s_mov_b32 s34, s40
	s_mov_b32 s35, s40
	v_pk_mul_f32 v[136:137], v[102:103], s[34:35]
	v_pk_mul_f32 v[138:139], v[100:101], s[40:41]
	s_mov_b64 s[66:67], 0

; __device__ __forceinline__ u32x2 pack4(f32x4 v) { u32x2 r; r[0] = cvt_pk(v[0], v[1]); r[1] = cvt_pk(v[2], v[3]); return r; }
; __device__ __forceinline__ float sigmoidf_(float x) { return __builtin_amdgcn_rcpf(1.0f + __expf(-x)); }
; __device__ __forceinline__ float gelu_tanh(float x) { const float z = 1.5957691216057308f * (x + 0.044715f * x * x * x); return x * sigmoidf_(z); }
; __device__ __forceinline__ float siluf_(float x) { return x * sigmoidf_(x); }
; __device__ __forceinline__ void epilogue(const Params& p, const Unit& u, const f32x4 (&acc)[2][2][4][2], int wr, int wc, int fr, int fq) {
;     ...
; #pragma unroll
;     for (int ai = 0; ai < 2; ++ai)
; #pragma unroll
;       for (int m = 0; m < 4; ++m) {
;         bf16_t* rp = dst + (size_t)(row0 + ai * 128 + m * 16) * ld + cb + ct0;
; #pragma unroll
;         for (int bj = 0; bj < 2; ++bj)
; #pragma unroll
;           for (int n = 0; n < 2; ++n) {
;             f32x4 v = acc[ai][bj][m][n];
;             if (act == 1) { v[0] = sigmoidf_(v[0]); v[1] = sigmoidf_(v[1]); v[2] = sigmoidf_(v[2]); v[3] = sigmoidf_(v[3]); }
;             else if (act == 2) { v[0] = gelu_tanh(v[0]); v[1] = gelu_tanh(v[1]); v[2] = gelu_tanh(v[2]); v[3] = gelu_tanh(v[3]); }
;             else if (act == 3) { v[0] = siluf_(v[0]); v[1] = siluf_(v[1]); v[2] = siluf_(v[2]); v[3] = siluf_(v[3]); }
;             else { v = v * scale; }
;             *(u32x2*)(rp + bj * 128 + n * 16) = pack4(v);
;           }
.LBB0_544:
	v_cvt_pk_bf16_f32 v138, v138, v139
	v_cvt_pk_bf16_f32 v139, v136, v137
	s_and_b64 vcc, exec, s[38:39]
	ds_bpermute_b32 v138, v140, v138
	ds_bpermute_b32 v139, v140, v139
	s_waitcnt lgkmcnt(0)
	global_store_dwordx2 v[134:135], v[138:139], off offset:32
	s_cbranch_vccnz .LBB0_756
	s_and_b64 vcc, exec, s[36:37]
	s_mov_b64 s[66:67], -1
	s_cbranch_vccnz .LBB0_551
	s_andn2_b64 vcc, exec, s[62:63]
	s_cbranch_vccnz .LBB0_548
	s_mov_b32 s34, s40
	s_mov_b32 s35, s40
	v_pk_mul_f32 v[136:137], v[74:75], s[34:35]
	v_pk_mul_f32 v[138:139], v[72:73], s[40:41]
	s_mov_b64 s[66:67], 0

; __device__ __forceinline__ u32x2 pack4(f32x4 v) { u32x2 r; r[0] = cvt_pk(v[0], v[1]); r[1] = cvt_pk(v[2], v[3]); return r; }
; __device__ __forceinline__ float sigmoidf_(float x) { return __builtin_amdgcn_rcpf(1.0f + __expf(-x)); }
; __device__ __forceinline__ float gelu_tanh(float x) { const float z = 1.5957691216057308f * (x + 0.044715f * x * x * x); return x * sigmoidf_(z); }
; __device__ __forceinline__ float siluf_(float x) { return x * sigmoidf_(x); }
; __device__ __forceinline__ void epilogue(const Params& p, const Unit& u, const f32x4 (&acc)[2][2][4][2], int wr, int wc, int fr, int fq) {
;     ...
; #pragma unroll
;     for (int ai = 0; ai < 2; ++ai)
; #pragma unroll
;       for (int m = 0; m < 4; ++m) {
;         bf16_t* rp = dst + (size_t)(row0 + ai * 128 + m * 16) * ld + cb + ct0;
; #pragma unroll
;         for (int bj = 0; bj < 2; ++bj)
; #pragma unroll
;           for (int n = 0; n < 2; ++n) {
;             f32x4 v = acc[ai][bj][m][n];
;             if (act == 1) { v[0] = sigmoidf_(v[0]); v[1] = sigmoidf_(v[1]); v[2] = sigmoidf_(v[2]); v[3] = sigmoidf_(v[3]); }
;             else if (act == 2) { v[0] = gelu_tanh(v[0]); v[1] = gelu_tanh(v[1]); v[2] = gelu_tanh(v[2]); v[3] = gelu_tanh(v[3]); }
;             else if (act == 3) { v[0] = siluf_(v[0]); v[1] = siluf_(v[1]); v[2] = siluf_(v[2]); v[3] = siluf_(v[3]); }
;             else { v = v * scale; }
;             *(u32x2*)(rp + bj * 128 + n * 16) = pack4(v);
;           }
.LBB0_555:
	v_cvt_pk_bf16_f32 v138, v138, v139
	v_cvt_pk_bf16_f32 v139, v136, v137
	s_and_b64 vcc, exec, s[38:39]
	ds_bpermute_b32 v138, v140, v138
	ds_bpermute_b32 v139, v140, v139
	s_waitcnt lgkmcnt(0)
	global_store_dwordx2 v[134:135], v[138:139], off offset:256
	s_cbranch_vccnz .LBB0_757
	s_and_b64 vcc, exec, s[36:37]
	s_mov_b64 s[66:67], -1
	s_cbranch_vccnz .LBB0_562
	s_andn2_b64 vcc, exec, s[62:63]
	s_cbranch_vccnz .LBB0_559
	s_mov_b32 s34, s40
	s_mov_b32 s35, s40
	v_pk_mul_f32 v[136:137], v[70:71], s[34:35]
	v_pk_mul_f32 v[138:139], v[68:69], s[40:41]
	s_mov_b64 s[66:67], 0

; __device__ __forceinline__ u32x2 pack4(f32x4 v) { u32x2 r; r[0] = cvt_pk(v[0], v[1]); r[1] = cvt_pk(v[2], v[3]); return r; }
; __device__ __forceinline__ float sigmoidf_(float x) { return __builtin_amdgcn_rcpf(1.0f + __expf(-x)); }
; __device__ __forceinline__ float gelu_tanh(float x) { const float z = 1.5957691216057308f * (x + 0.044715f * x * x * x); return x * sigmoidf_(z); }
; __device__ __forceinline__ float siluf_(float x) { return x * sigmoidf_(x); }
; __device__ __forceinline__ void epilogue(const Params& p, const Unit& u, const f32x4 (&acc)[2][2][4][2], int wr, int wc, int fr, int fq) {
;     ...
; #pragma unroll
;     for (int ai = 0; ai < 2; ++ai)
; #pragma unroll
;       for (int m = 0; m < 4; ++m) {
;         bf16_t* rp = dst + (size_t)(row0 + ai * 128 + m * 16) * ld + cb + ct0;
; #pragma unroll
;         for (int bj = 0; bj < 2; ++bj)
; #pragma unroll
;           for (int n = 0; n < 2; ++n) {
;             f32x4 v = acc[ai][bj][m][n];
;             if (act == 1) { v[0] = sigmoidf_(v[0]); v[1] = sigmoidf_(v[1]); v[2] = sigmoidf_(v[2]); v[3] = sigmoidf_(v[3]); }
;             else if (act == 2) { v[0] = gelu_tanh(v[0]); v[1] = gelu_tanh(v[1]); v[2] = gelu_tanh(v[2]); v[3] = gelu_tanh(v[3]); }
;             else if (act == 3) { v[0] = siluf_(v[0]); v[1] = siluf_(v[1]); v[2] = siluf_(v[2]); v[3] = siluf_(v[3]); }
;             else { v = v * scale; }
;             *(u32x2*)(rp + bj * 128 + n * 16) = pack4(v);
;           }
.LBB0_566:
	v_cvt_pk_bf16_f32 v138, v138, v139
	v_cvt_pk_bf16_f32 v139, v136, v137
	s_and_b64 vcc, exec, s[38:39]
	ds_bpermute_b32 v138, v140, v138
	ds_bpermute_b32 v139, v140, v139
	s_waitcnt lgkmcnt(0)
	global_store_dwordx2 v[134:135], v[138:139], off offset:288
	s_cbranch_vccnz .LBB0_758
	s_and_b64 vcc, exec, s[36:37]
	s_mov_b64 s[66:67], -1
	s_cbranch_vccnz .LBB0_573
	s_andn2_b64 vcc, exec, s[62:63]
	s_cbranch_vccnz .LBB0_570
	s_mov_b32 s34, s40
	s_mov_b32 s35, s40
	v_pk_mul_f32 v[136:137], v[62:63], s[34:35]
	v_pk_mul_f32 v[138:139], v[60:61], s[40:41]
	s_mov_b64 s[66:67], 0

; __device__ __forceinline__ u32x2 pack4(f32x4 v) { u32x2 r; r[0] = cvt_pk(v[0], v[1]); r[1] = cvt_pk(v[2], v[3]); return r; }
; __device__ __forceinline__ float sigmoidf_(float x) { return __builtin_amdgcn_rcpf(1.0f + __expf(-x)); }
; __device__ __forceinline__ float gelu_tanh(float x) { const float z = 1.5957691216057308f * (x + 0.044715f * x * x * x); return x * sigmoidf_(z); }
; __device__ __forceinline__ float siluf_(float x) { return x * sigmoidf_(x); }
; __device__ __forceinline__ void epilogue(const Params& p, const Unit& u, const f32x4 (&acc)[2][2][4][2], int wr, int wc, int fr, int fq) {
;     ...
; #pragma unroll
;     for (int ai = 0; ai < 2; ++ai)
; #pragma unroll
;       for (int m = 0; m < 4; ++m) {
;         bf16_t* rp = dst + (size_t)(row0 + ai * 128 + m * 16) * ld + cb + ct0;
; #pragma unroll
;         for (int bj = 0; bj < 2; ++bj)
; #pragma unroll
;           for (int n = 0; n < 2; ++n) {
;             f32x4 v = acc[ai][bj][m][n];
;             if (act == 1) { v[0] = sigmoidf_(v[0]); v[1] = sigmoidf_(v[1]); v[2] = sigmoidf_(v[2]); v[3] = sigmoidf_(v[3]); }
;             else if (act == 2) { v[0] = gelu_tanh(v[0]); v[1] = gelu_tanh(v[1]); v[2] = gelu_tanh(v[2]); v[3] = gelu_tanh(v[3]); }
;             else if (act == 3) { v[0] = siluf_(v[0]); v[1] = siluf_(v[1]); v[2] = siluf_(v[2]); v[3] = siluf_(v[3]); }
;             else { v = v * scale; }
;             *(u32x2*)(rp + bj * 128 + n * 16) = pack4(v);
;           }
.LBB0_577:
	v_add_u32_e32 v64, 0x80, v66
	v_mad_i64_i32 v[134:135], s[34:35], s64, v64, 0
	v_lshl_add_u64 v[134:135], v[134:135], 1, v[132:133]
	v_cvt_pk_bf16_f32 v138, v138, v139
	v_cvt_pk_bf16_f32 v139, v136, v137
	s_and_b64 vcc, exec, s[38:39]
	ds_bpermute_b32 v138, v140, v138
	ds_bpermute_b32 v139, v140, v139
	s_waitcnt lgkmcnt(0)
	global_store_dwordx2 v[134:135], v[138:139], off
	s_cbranch_vccnz .LBB0_759
	s_and_b64 vcc, exec, s[36:37]
	s_mov_b64 s[66:67], -1
	s_cbranch_vccnz .LBB0_584
	s_andn2_b64 vcc, exec, s[62:63]
	s_cbranch_vccnz .LBB0_581
	s_mov_b32 s34, s40
	s_mov_b32 s35, s40
	v_pk_mul_f32 v[136:137], v[58:59], s[34:35]
	v_pk_mul_f32 v[138:139], v[56:57], s[40:41]
	s_mov_b64 s[66:67], 0

; __device__ __forceinline__ u32x2 pack4(f32x4 v) { u32x2 r; r[0] = cvt_pk(v[0], v[1]); r[1] = cvt_pk(v[2], v[3]); return r; }
; __device__ __forceinline__ float sigmoidf_(float x) { return __builtin_amdgcn_rcpf(1.0f + __expf(-x)); }
; __device__ __forceinline__ float gelu_tanh(float x) { const float z = 1.5957691216057308f * (x + 0.044715f * x * x * x); return x * sigmoidf_(z); }
; __device__ __forceinline__ float siluf_(float x) { return x * sigmoidf_(x); }
; __device__ __forceinline__ void epilogue(const Params& p, const Unit& u, const f32x4 (&acc)[2][2][4][2], int wr, int wc, int fr, int fq) {
;     ...
; #pragma unroll
;     for (int ai = 0; ai < 2; ++ai)
; #pragma unroll
;       for (int m = 0; m < 4; ++m) {
;         bf16_t* rp = dst + (size_t)(row0 + ai * 128 + m * 16) * ld + cb + ct0;
; #pragma unroll
;         for (int bj = 0; bj < 2; ++bj)
; #pragma unroll
;           for (int n = 0; n < 2; ++n) {
;             f32x4 v = acc[ai][bj][m][n];
;             if (act == 1) { v[0] = sigmoidf_(v[0]); v[1] = sigmoidf_(v[1]); v[2] = sigmoidf_(v[2]); v[3] = sigmoidf_(v[3]); }
;             else if (act == 2) { v[0] = gelu_tanh(v[0]); v[1] = gelu_tanh(v[1]); v[2] = gelu_tanh(v[2]); v[3] = gelu_tanh(v[3]); }
;             else if (act == 3) { v[0] = siluf_(v[0]); v[1] = siluf_(v[1]); v[2] = siluf_(v[2]); v[3] = siluf_(v[3]); }
;             else { v = v * scale; }
;             *(u32x2*)(rp + bj * 128 + n * 16) = pack4(v);
;           }
.LBB0_588:
	v_cvt_pk_bf16_f32 v138, v138, v139
	v_cvt_pk_bf16_f32 v139, v136, v137
	s_and_b64 vcc, exec, s[38:39]
	ds_bpermute_b32 v138, v140, v138
	ds_bpermute_b32 v139, v140, v139
	s_waitcnt lgkmcnt(0)
	global_store_dwordx2 v[134:135], v[138:139], off offset:32
	s_cbranch_vccnz .LBB0_760
	s_and_b64 vcc, exec, s[36:37]
	s_mov_b64 s[66:67], -1
	s_cbranch_vccnz .LBB0_595
	s_andn2_b64 vcc, exec, s[62:63]
	s_cbranch_vccnz .LBB0_592
	s_mov_b32 s34, s40
	s_mov_b32 s35, s40
	v_pk_mul_f32 v[136:137], v[30:31], s[34:35]
	v_pk_mul_f32 v[138:139], v[28:29], s[40:41]
	s_mov_b64 s[66:67], 0

; __device__ __forceinline__ u32x2 pack4(f32x4 v) { u32x2 r; r[0] = cvt_pk(v[0], v[1]); r[1] = cvt_pk(v[2], v[3]); return r; }
; __device__ __forceinline__ float sigmoidf_(float x) { return __builtin_amdgcn_rcpf(1.0f + __expf(-x)); }
; __device__ __forceinline__ float gelu_tanh(float x) { const float z = 1.5957691216057308f * (x + 0.044715f * x * x * x); return x * sigmoidf_(z); }
; __device__ __forceinline__ float siluf_(float x) { return x * sigmoidf_(x); }
; __device__ __forceinline__ void epilogue(const Params& p, const Unit& u, const f32x4 (&acc)[2][2][4][2], int wr, int wc, int fr, int fq) {
;     ...
; #pragma unroll
;     for (int ai = 0; ai < 2; ++ai)
; #pragma unroll
;       for (int m = 0; m < 4; ++m) {
;         bf16_t* rp = dst + (size_t)(row0 + ai * 128 + m * 16) * ld + cb + ct0;
; #pragma unroll
;         for (int bj = 0; bj < 2; ++bj)
; #pragma unroll
;           for (int n = 0; n < 2; ++n) {
;             f32x4 v = acc[ai][bj][m][n];
;             if (act == 1) { v[0] = sigmoidf_(v[0]); v[1] = sigmoidf_(v[1]); v[2] = sigmoidf_(v[2]); v[3] = sigmoidf_(v[3]); }
;             else if (act == 2) { v[0] = gelu_tanh(v[0]); v[1] = gelu_tanh(v[1]); v[2] = gelu_tanh(v[2]); v[3] = gelu_tanh(v[3]); }
;             else if (act == 3) { v[0] = siluf_(v[0]); v[1] = siluf_(v[1]); v[2] = siluf_(v[2]); v[3] = siluf_(v[3]); }
;             else { v = v * scale; }
;             *(u32x2*)(rp + bj * 128 + n * 16) = pack4(v);
;           }
.LBB0_599:
	v_cvt_pk_bf16_f32 v138, v138, v139
	v_cvt_pk_bf16_f32 v139, v136, v137
	s_and_b64 vcc, exec, s[38:39]
	ds_bpermute_b32 v138, v140, v138
	ds_bpermute_b32 v139, v140, v139
	s_waitcnt lgkmcnt(0)
	global_store_dwordx2 v[134:135], v[138:139], off offset:256
	s_cbranch_vccnz .LBB0_761
	s_and_b64 vcc, exec, s[36:37]
	s_mov_b64 s[66:67], -1
	s_cbranch_vccnz .LBB0_606
	s_andn2_b64 vcc, exec, s[62:63]
	s_cbranch_vccnz .LBB0_603
	s_mov_b32 s34, s40
	s_mov_b32 s35, s40
	v_pk_mul_f32 v[136:137], v[26:27], s[34:35]
	v_pk_mul_f32 v[138:139], v[24:25], s[40:41]
	s_mov_b64 s[66:67], 0

; __device__ __forceinline__ u32x2 pack4(f32x4 v) { u32x2 r; r[0] = cvt_pk(v[0], v[1]); r[1] = cvt_pk(v[2], v[3]); return r; }
; __device__ __forceinline__ float sigmoidf_(float x) { return __builtin_amdgcn_rcpf(1.0f + __expf(-x)); }
; __device__ __forceinline__ float gelu_tanh(float x) { const float z = 1.5957691216057308f * (x + 0.044715f * x * x * x); return x * sigmoidf_(z); }
; __device__ __forceinline__ float siluf_(float x) { return x * sigmoidf_(x); }
; __device__ __forceinline__ void epilogue(const Params& p, const Unit& u, const f32x4 (&acc)[2][2][4][2], int wr, int wc, int fr, int fq) {
;     ...
; #pragma unroll
;     for (int ai = 0; ai < 2; ++ai)
; #pragma unroll
;       for (int m = 0; m < 4; ++m) {
;         bf16_t* rp = dst + (size_t)(row0 + ai * 128 + m * 16) * ld + cb + ct0;
; #pragma unroll
;         for (int bj = 0; bj < 2; ++bj)
; #pragma unroll
;           for (int n = 0; n < 2; ++n) {
;             f32x4 v = acc[ai][bj][m][n];
;             if (act == 1) { v[0] = sigmoidf_(v[0]); v[1] = sigmoidf_(v[1]); v[2] = sigmoidf_(v[2]); v[3] = sigmoidf_(v[3]); }
;             else if (act == 2) { v[0] = gelu_tanh(v[0]); v[1] = gelu_tanh(v[1]); v[2] = gelu_tanh(v[2]); v[3] = gelu_tanh(v[3]); }
;             else if (act == 3) { v[0] = siluf_(v[0]); v[1] = siluf_(v[1]); v[2] = siluf_(v[2]); v[3] = siluf_(v[3]); }
;             else { v = v * scale; }
;             *(u32x2*)(rp + bj * 128 + n * 16) = pack4(v);
;           }
.LBB0_610:
	v_cvt_pk_bf16_f32 v138, v138, v139
	v_cvt_pk_bf16_f32 v139, v136, v137
	s_and_b64 vcc, exec, s[38:39]
	ds_bpermute_b32 v138, v140, v138
	ds_bpermute_b32 v139, v140, v139
	s_waitcnt lgkmcnt(0)
	global_store_dwordx2 v[134:135], v[138:139], off offset:288
	s_cbranch_vccnz .LBB0_762
	s_and_b64 vcc, exec, s[36:37]
	s_mov_b64 s[66:67], -1
	s_cbranch_vccnz .LBB0_617
	s_andn2_b64 vcc, exec, s[62:63]
	s_cbranch_vccnz .LBB0_614
	s_mov_b32 s34, s40
	s_mov_b32 s35, s40
	v_pk_mul_f32 v[136:137], v[54:55], s[34:35]
	v_pk_mul_f32 v[138:139], v[52:53], s[40:41]
	s_mov_b64 s[66:67], 0

; __device__ __forceinline__ u32x2 pack4(f32x4 v) { u32x2 r; r[0] = cvt_pk(v[0], v[1]); r[1] = cvt_pk(v[2], v[3]); return r; }
; __device__ __forceinline__ float sigmoidf_(float x) { return __builtin_amdgcn_rcpf(1.0f + __expf(-x)); }
; __device__ __forceinline__ float gelu_tanh(float x) { const float z = 1.5957691216057308f * (x + 0.044715f * x * x * x); return x * sigmoidf_(z); }
; __device__ __forceinline__ float siluf_(float x) { return x * sigmoidf_(x); }
; __device__ __forceinline__ void epilogue(const Params& p, const Unit& u, const f32x4 (&acc)[2][2][4][2], int wr, int wc, int fr, int fq) {
;     ...
; #pragma unroll
;     for (int ai = 0; ai < 2; ++ai)
; #pragma unroll
;       for (int m = 0; m < 4; ++m) {
;         bf16_t* rp = dst + (size_t)(row0 + ai * 128 + m * 16) * ld + cb + ct0;
; #pragma unroll
;         for (int bj = 0; bj < 2; ++bj)
; #pragma unroll
;           for (int n = 0; n < 2; ++n) {
;             f32x4 v = acc[ai][bj][m][n];
;             if (act == 1) { v[0] = sigmoidf_(v[0]); v[1] = sigmoidf_(v[1]); v[2] = sigmoidf_(v[2]); v[3] = sigmoidf_(v[3]); }
;             else if (act == 2) { v[0] = gelu_tanh(v[0]); v[1] = gelu_tanh(v[1]); v[2] = gelu_tanh(v[2]); v[3] = gelu_tanh(v[3]); }
;             else if (act == 3) { v[0] = siluf_(v[0]); v[1] = siluf_(v[1]); v[2] = siluf_(v[2]); v[3] = siluf_(v[3]); }
;             else { v = v * scale; }
;             *(u32x2*)(rp + bj * 128 + n * 16) = pack4(v);
;           }
.LBB0_621:
	v_add_u32_e32 v64, 0x90, v66
	v_mad_i64_i32 v[134:135], s[34:35], s64, v64, 0
	v_lshl_add_u64 v[134:135], v[134:135], 1, v[132:133]
	v_cvt_pk_bf16_f32 v138, v138, v139
	v_cvt_pk_bf16_f32 v139, v136, v137
	s_and_b64 vcc, exec, s[38:39]
	ds_bpermute_b32 v138, v140, v138
	ds_bpermute_b32 v139, v140, v139
	s_waitcnt lgkmcnt(0)
	global_store_dwordx2 v[134:135], v[138:139], off
	s_cbranch_vccnz .LBB0_763
	s_and_b64 vcc, exec, s[36:37]
	s_mov_b64 s[66:67], -1
	s_cbranch_vccnz .LBB0_628
	s_andn2_b64 vcc, exec, s[62:63]
	s_cbranch_vccnz .LBB0_625
	s_mov_b32 s34, s40
	s_mov_b32 s35, s40
	v_pk_mul_f32 v[136:137], v[50:51], s[34:35]
	v_pk_mul_f32 v[138:139], v[48:49], s[40:41]
	s_mov_b64 s[66:67], 0

; __device__ __forceinline__ u32x2 pack4(f32x4 v) { u32x2 r; r[0] = cvt_pk(v[0], v[1]); r[1] = cvt_pk(v[2], v[3]); return r; }
; __device__ __forceinline__ float sigmoidf_(float x) { return __builtin_amdgcn_rcpf(1.0f + __expf(-x)); }
; __device__ __forceinline__ float gelu_tanh(float x) { const float z = 1.5957691216057308f * (x + 0.044715f * x * x * x); return x * sigmoidf_(z); }
; __device__ __forceinline__ float siluf_(float x) { return x * sigmoidf_(x); }
; __device__ __forceinline__ void epilogue(const Params& p, const Unit& u, const f32x4 (&acc)[2][2][4][2], int wr, int wc, int fr, int fq) {
;     ...
; #pragma unroll
;     for (int ai = 0; ai < 2; ++ai)
; #pragma unroll
;       for (int m = 0; m < 4; ++m) {
;         bf16_t* rp = dst + (size_t)(row0 + ai * 128 + m * 16) * ld + cb + ct0;
; #pragma unroll
;         for (int bj = 0; bj < 2; ++bj)
; #pragma unroll
;           for (int n = 0; n < 2; ++n) {
;             f32x4 v = acc[ai][bj][m][n];
;             if (act == 1) { v[0] = sigmoidf_(v[0]); v[1] = sigmoidf_(v[1]); v[2] = sigmoidf_(v[2]); v[3] = sigmoidf_(v[3]); }
;             else if (act == 2) { v[0] = gelu_tanh(v[0]); v[1] = gelu_tanh(v[1]); v[2] = gelu_tanh(v[2]); v[3] = gelu_tanh(v[3]); }
;             else if (act == 3) { v[0] = siluf_(v[0]); v[1] = siluf_(v[1]); v[2] = siluf_(v[2]); v[3] = siluf_(v[3]); }
;             else { v = v * scale; }
;             *(u32x2*)(rp + bj * 128 + n * 16) = pack4(v);
;           }
.LBB0_632:
	v_cvt_pk_bf16_f32 v138, v138, v139
	v_cvt_pk_bf16_f32 v139, v136, v137
	s_and_b64 vcc, exec, s[38:39]
	ds_bpermute_b32 v138, v140, v138
	ds_bpermute_b32 v139, v140, v139
	s_waitcnt lgkmcnt(0)
	global_store_dwordx2 v[134:135], v[138:139], off offset:32
	s_cbranch_vccnz .LBB0_764
	s_and_b64 vcc, exec, s[36:37]
	s_mov_b64 s[66:67], -1
	s_cbranch_vccnz .LBB0_639
	s_andn2_b64 vcc, exec, s[62:63]
	s_cbranch_vccnz .LBB0_636
	s_mov_b32 s34, s40
	s_mov_b32 s35, s40
	v_pk_mul_f32 v[136:137], v[22:23], s[34:35]
	v_pk_mul_f32 v[138:139], v[20:21], s[40:41]
	s_mov_b64 s[66:67], 0

; __device__ __forceinline__ u32x2 pack4(f32x4 v) { u32x2 r; r[0] = cvt_pk(v[0], v[1]); r[1] = cvt_pk(v[2], v[3]); return r; }
; __device__ __forceinline__ float sigmoidf_(float x) { return __builtin_amdgcn_rcpf(1.0f + __expf(-x)); }
; __device__ __forceinline__ float gelu_tanh(float x) { const float z = 1.5957691216057308f * (x + 0.044715f * x * x * x); return x * sigmoidf_(z); }
; __device__ __forceinline__ float siluf_(float x) { return x * sigmoidf_(x); }
; __device__ __forceinline__ void epilogue(const Params& p, const Unit& u, const f32x4 (&acc)[2][2][4][2], int wr, int wc, int fr, int fq) {
;     ...
; #pragma unroll
;     for (int ai = 0; ai < 2; ++ai)
; #pragma unroll
;       for (int m = 0; m < 4; ++m) {
;         bf16_t* rp = dst + (size_t)(row0 + ai * 128 + m * 16) * ld + cb + ct0;
; #pragma unroll
;         for (int bj = 0; bj < 2; ++bj)
; #pragma unroll
;           for (int n = 0; n < 2; ++n) {
;             f32x4 v = acc[ai][bj][m][n];
;             if (act == 1) { v[0] = sigmoidf_(v[0]); v[1] = sigmoidf_(v[1]); v[2] = sigmoidf_(v[2]); v[3] = sigmoidf_(v[3]); }
;             else if (act == 2) { v[0] = gelu_tanh(v[0]); v[1] = gelu_tanh(v[1]); v[2] = gelu_tanh(v[2]); v[3] = gelu_tanh(v[3]); }
;             else if (act == 3) { v[0] = siluf_(v[0]); v[1] = siluf_(v[1]); v[2] = siluf_(v[2]); v[3] = siluf_(v[3]); }
;             else { v = v * scale; }
;             *(u32x2*)(rp + bj * 128 + n * 16) = pack4(v);
;           }
.LBB0_643:
	v_cvt_pk_bf16_f32 v138, v138, v139
	v_cvt_pk_bf16_f32 v139, v136, v137
	s_and_b64 vcc, exec, s[38:39]
	ds_bpermute_b32 v138, v140, v138
	ds_bpermute_b32 v139, v140, v139
	s_waitcnt lgkmcnt(0)
	global_store_dwordx2 v[134:135], v[138:139], off offset:256
	s_cbranch_vccnz .LBB0_765
	s_and_b64 vcc, exec, s[36:37]
	s_mov_b64 s[66:67], -1
	s_cbranch_vccnz .LBB0_650
	s_andn2_b64 vcc, exec, s[62:63]
	s_cbranch_vccnz .LBB0_647
	s_mov_b32 s34, s40
	s_mov_b32 s35, s40
	v_pk_mul_f32 v[136:137], v[18:19], s[34:35]
	v_pk_mul_f32 v[138:139], v[16:17], s[40:41]
	s_mov_b64 s[66:67], 0

; __device__ __forceinline__ u32x2 pack4(f32x4 v) { u32x2 r; r[0] = cvt_pk(v[0], v[1]); r[1] = cvt_pk(v[2], v[3]); return r; }
; __device__ __forceinline__ float sigmoidf_(float x) { return __builtin_amdgcn_rcpf(1.0f + __expf(-x)); }
; __device__ __forceinline__ float gelu_tanh(float x) { const float z = 1.5957691216057308f * (x + 0.044715f * x * x * x); return x * sigmoidf_(z); }
; __device__ __forceinline__ float siluf_(float x) { return x * sigmoidf_(x); }
; __device__ __forceinline__ void epilogue(const Params& p, const Unit& u, const f32x4 (&acc)[2][2][4][2], int wr, int wc, int fr, int fq) {
;     ...
; #pragma unroll
;     for (int ai = 0; ai < 2; ++ai)
; #pragma unroll
;       for (int m = 0; m < 4; ++m) {
;         bf16_t* rp = dst + (size_t)(row0 + ai * 128 + m * 16) * ld + cb + ct0;
; #pragma unroll
;         for (int bj = 0; bj < 2; ++bj)
; #pragma unroll
;           for (int n = 0; n < 2; ++n) {
;             f32x4 v = acc[ai][bj][m][n];
;             if (act == 1) { v[0] = sigmoidf_(v[0]); v[1] = sigmoidf_(v[1]); v[2] = sigmoidf_(v[2]); v[3] = sigmoidf_(v[3]); }
;             else if (act == 2) { v[0] = gelu_tanh(v[0]); v[1] = gelu_tanh(v[1]); v[2] = gelu_tanh(v[2]); v[3] = gelu_tanh(v[3]); }
;             else if (act == 3) { v[0] = siluf_(v[0]); v[1] = siluf_(v[1]); v[2] = siluf_(v[2]); v[3] = siluf_(v[3]); }
;             else { v = v * scale; }
;             *(u32x2*)(rp + bj * 128 + n * 16) = pack4(v);
;           }
.LBB0_654:
	v_cvt_pk_bf16_f32 v138, v138, v139
	v_cvt_pk_bf16_f32 v139, v136, v137
	s_and_b64 vcc, exec, s[38:39]
	ds_bpermute_b32 v138, v140, v138
	ds_bpermute_b32 v139, v140, v139
	s_waitcnt lgkmcnt(0)
	global_store_dwordx2 v[134:135], v[138:139], off offset:288
	s_cbranch_vccnz .LBB0_766
	s_and_b64 vcc, exec, s[36:37]
	s_mov_b64 s[66:67], -1
	s_cbranch_vccnz .LBB0_661
	s_andn2_b64 vcc, exec, s[62:63]
	s_cbranch_vccnz .LBB0_658
	s_mov_b32 s34, s40
	s_mov_b32 s35, s40
	v_pk_mul_f32 v[136:137], v[46:47], s[34:35]
	v_pk_mul_f32 v[138:139], v[44:45], s[40:41]
	s_mov_b64 s[66:67], 0

; __device__ __forceinline__ u32x2 pack4(f32x4 v) { u32x2 r; r[0] = cvt_pk(v[0], v[1]); r[1] = cvt_pk(v[2], v[3]); return r; }
; __device__ __forceinline__ float sigmoidf_(float x) { return __builtin_amdgcn_rcpf(1.0f + __expf(-x)); }
; __device__ __forceinline__ float gelu_tanh(float x) { const float z = 1.5957691216057308f * (x + 0.044715f * x * x * x); return x * sigmoidf_(z); }
; __device__ __forceinline__ float siluf_(float x) { return x * sigmoidf_(x); }
; __device__ __forceinline__ void epilogue(const Params& p, const Unit& u, const f32x4 (&acc)[2][2][4][2], int wr, int wc, int fr, int fq) {
;     ...
; #pragma unroll
;     for (int ai = 0; ai < 2; ++ai)
; #pragma unroll
;       for (int m = 0; m < 4; ++m) {
;         bf16_t* rp = dst + (size_t)(row0 + ai * 128 + m * 16) * ld + cb + ct0;
; #pragma unroll
;         for (int bj = 0; bj < 2; ++bj)
; #pragma unroll
;           for (int n = 0; n < 2; ++n) {
;             f32x4 v = acc[ai][bj][m][n];
;             if (act == 1) { v[0] = sigmoidf_(v[0]); v[1] = sigmoidf_(v[1]); v[2] = sigmoidf_(v[2]); v[3] = sigmoidf_(v[3]); }
;             else if (act == 2) { v[0] = gelu_tanh(v[0]); v[1] = gelu_tanh(v[1]); v[2] = gelu_tanh(v[2]); v[3] = gelu_tanh(v[3]); }
;             else if (act == 3) { v[0] = siluf_(v[0]); v[1] = siluf_(v[1]); v[2] = siluf_(v[2]); v[3] = siluf_(v[3]); }
;             else { v = v * scale; }
;             *(u32x2*)(rp + bj * 128 + n * 16) = pack4(v);
;           }
.LBB0_665:
	v_add_u32_e32 v64, 0xa0, v66
	v_mad_i64_i32 v[134:135], s[34:35], s64, v64, 0
	v_lshl_add_u64 v[134:135], v[134:135], 1, v[132:133]
	v_cvt_pk_bf16_f32 v138, v138, v139
	v_cvt_pk_bf16_f32 v139, v136, v137
	s_and_b64 vcc, exec, s[38:39]
	ds_bpermute_b32 v138, v140, v138
	ds_bpermute_b32 v139, v140, v139
	s_waitcnt lgkmcnt(0)
	global_store_dwordx2 v[134:135], v[138:139], off
	s_cbranch_vccnz .LBB0_767
	s_and_b64 vcc, exec, s[36:37]
	s_mov_b64 s[66:67], -1
	s_cbranch_vccnz .LBB0_672
	s_andn2_b64 vcc, exec, s[62:63]
	s_cbranch_vccnz .LBB0_669
	s_mov_b32 s34, s40
	s_mov_b32 s35, s40
	v_pk_mul_f32 v[136:137], v[42:43], s[34:35]
	v_pk_mul_f32 v[138:139], v[40:41], s[40:41]
	s_mov_b64 s[66:67], 0

; __device__ __forceinline__ u32x2 pack4(f32x4 v) { u32x2 r; r[0] = cvt_pk(v[0], v[1]); r[1] = cvt_pk(v[2], v[3]); return r; }
; __device__ __forceinline__ float sigmoidf_(float x) { return __builtin_amdgcn_rcpf(1.0f + __expf(-x)); }
; __device__ __forceinline__ float gelu_tanh(float x) { const float z = 1.5957691216057308f * (x + 0.044715f * x * x * x); return x * sigmoidf_(z); }
; __device__ __forceinline__ float siluf_(float x) { return x * sigmoidf_(x); }
; __device__ __forceinline__ void epilogue(const Params& p, const Unit& u, const f32x4 (&acc)[2][2][4][2], int wr, int wc, int fr, int fq) {
;     ...
; #pragma unroll
;     for (int ai = 0; ai < 2; ++ai)
; #pragma unroll
;       for (int m = 0; m < 4; ++m) {
;         bf16_t* rp = dst + (size_t)(row0 + ai * 128 + m * 16) * ld + cb + ct0;
; #pragma unroll
;         for (int bj = 0; bj < 2; ++bj)
; #pragma unroll
;           for (int n = 0; n < 2; ++n) {
;             f32x4 v = acc[ai][bj][m][n];
;             if (act == 1) { v[0] = sigmoidf_(v[0]); v[1] = sigmoidf_(v[1]); v[2] = sigmoidf_(v[2]); v[3] = sigmoidf_(v[3]); }
;             else if (act == 2) { v[0] = gelu_tanh(v[0]); v[1] = gelu_tanh(v[1]); v[2] = gelu_tanh(v[2]); v[3] = gelu_tanh(v[3]); }
;             else if (act == 3) { v[0] = siluf_(v[0]); v[1] = siluf_(v[1]); v[2] = siluf_(v[2]); v[3] = siluf_(v[3]); }
;             else { v = v * scale; }
;             *(u32x2*)(rp + bj * 128 + n * 16) = pack4(v);
;           }
.LBB0_676:
	v_cvt_pk_bf16_f32 v138, v138, v139
	v_cvt_pk_bf16_f32 v139, v136, v137
	s_and_b64 vcc, exec, s[38:39]
	ds_bpermute_b32 v138, v140, v138
	ds_bpermute_b32 v139, v140, v139
	s_waitcnt lgkmcnt(0)
	global_store_dwordx2 v[134:135], v[138:139], off offset:32
	s_cbranch_vccnz .LBB0_768
	s_and_b64 vcc, exec, s[36:37]
	s_mov_b64 s[66:67], -1
	s_cbranch_vccnz .LBB0_683
	s_andn2_b64 vcc, exec, s[62:63]
	s_cbranch_vccnz .LBB0_680
	s_mov_b32 s34, s40
	s_mov_b32 s35, s40
	v_pk_mul_f32 v[136:137], v[14:15], s[34:35]
	v_pk_mul_f32 v[138:139], v[12:13], s[40:41]
	s_mov_b64 s[66:67], 0

; __device__ __forceinline__ u32x2 pack4(f32x4 v) { u32x2 r; r[0] = cvt_pk(v[0], v[1]); r[1] = cvt_pk(v[2], v[3]); return r; }
; __device__ __forceinline__ float sigmoidf_(float x) { return __builtin_amdgcn_rcpf(1.0f + __expf(-x)); }
; __device__ __forceinline__ float gelu_tanh(float x) { const float z = 1.5957691216057308f * (x + 0.044715f * x * x * x); return x * sigmoidf_(z); }
; __device__ __forceinline__ float siluf_(float x) { return x * sigmoidf_(x); }
; __device__ __forceinline__ void epilogue(const Params& p, const Unit& u, const f32x4 (&acc)[2][2][4][2], int wr, int wc, int fr, int fq) {
;     ...
; #pragma unroll
;     for (int ai = 0; ai < 2; ++ai)
; #pragma unroll
;       for (int m = 0; m < 4; ++m) {
;         bf16_t* rp = dst + (size_t)(row0 + ai * 128 + m * 16) * ld + cb + ct0;
; #pragma unroll
;         for (int bj = 0; bj < 2; ++bj)
; #pragma unroll
;           for (int n = 0; n < 2; ++n) {
;             f32x4 v = acc[ai][bj][m][n];
;             if (act == 1) { v[0] = sigmoidf_(v[0]); v[1] = sigmoidf_(v[1]); v[2] = sigmoidf_(v[2]); v[3] = sigmoidf_(v[3]); }
;             else if (act == 2) { v[0] = gelu_tanh(v[0]); v[1] = gelu_tanh(v[1]); v[2] = gelu_tanh(v[2]); v[3] = gelu_tanh(v[3]); }
;             else if (act == 3) { v[0] = siluf_(v[0]); v[1] = siluf_(v[1]); v[2] = siluf_(v[2]); v[3] = siluf_(v[3]); }
;             else { v = v * scale; }
;             *(u32x2*)(rp + bj * 128 + n * 16) = pack4(v);
;           }
.LBB0_687:
	v_cvt_pk_bf16_f32 v138, v138, v139
	v_cvt_pk_bf16_f32 v139, v136, v137
	s_and_b64 vcc, exec, s[38:39]
	ds_bpermute_b32 v138, v140, v138
	ds_bpermute_b32 v139, v140, v139
	s_waitcnt lgkmcnt(0)
	global_store_dwordx2 v[134:135], v[138:139], off offset:256
	s_cbranch_vccnz .LBB0_769
	s_and_b64 vcc, exec, s[36:37]
	s_mov_b64 s[66:67], -1
	s_cbranch_vccnz .LBB0_694
	s_andn2_b64 vcc, exec, s[62:63]
	s_cbranch_vccnz .LBB0_691
	s_mov_b32 s34, s40
	s_mov_b32 s35, s40
	v_pk_mul_f32 v[136:137], v[10:11], s[34:35]
	v_pk_mul_f32 v[138:139], v[8:9], s[40:41]
	s_mov_b64 s[66:67], 0

; __device__ __forceinline__ u32x2 pack4(f32x4 v) { u32x2 r; r[0] = cvt_pk(v[0], v[1]); r[1] = cvt_pk(v[2], v[3]); return r; }
; __device__ __forceinline__ float sigmoidf_(float x) { return __builtin_amdgcn_rcpf(1.0f + __expf(-x)); }
; __device__ __forceinline__ float gelu_tanh(float x) { const float z = 1.5957691216057308f * (x + 0.044715f * x * x * x); return x * sigmoidf_(z); }
; __device__ __forceinline__ float siluf_(float x) { return x * sigmoidf_(x); }
; __device__ __forceinline__ void epilogue(const Params& p, const Unit& u, const f32x4 (&acc)[2][2][4][2], int wr, int wc, int fr, int fq) {
;     ...
; #pragma unroll
;     for (int ai = 0; ai < 2; ++ai)
; #pragma unroll
;       for (int m = 0; m < 4; ++m) {
;         bf16_t* rp = dst + (size_t)(row0 + ai * 128 + m * 16) * ld + cb + ct0;
; #pragma unroll
;         for (int bj = 0; bj < 2; ++bj)
; #pragma unroll
;           for (int n = 0; n < 2; ++n) {
;             f32x4 v = acc[ai][bj][m][n];
;             if (act == 1) { v[0] = sigmoidf_(v[0]); v[1] = sigmoidf_(v[1]); v[2] = sigmoidf_(v[2]); v[3] = sigmoidf_(v[3]); }
;             else if (act == 2) { v[0] = gelu_tanh(v[0]); v[1] = gelu_tanh(v[1]); v[2] = gelu_tanh(v[2]); v[3] = gelu_tanh(v[3]); }
;             else if (act == 3) { v[0] = siluf_(v[0]); v[1] = siluf_(v[1]); v[2] = siluf_(v[2]); v[3] = siluf_(v[3]); }
;             else { v = v * scale; }
;             *(u32x2*)(rp + bj * 128 + n * 16) = pack4(v);
;           }
.LBB0_698:
	v_cvt_pk_bf16_f32 v138, v138, v139
	v_cvt_pk_bf16_f32 v139, v136, v137
	s_and_b64 vcc, exec, s[38:39]
	ds_bpermute_b32 v138, v140, v138
	ds_bpermute_b32 v139, v140, v139
	s_waitcnt lgkmcnt(0)
	global_store_dwordx2 v[134:135], v[138:139], off offset:288
	s_cbranch_vccnz .LBB0_770
	s_and_b64 vcc, exec, s[36:37]
	s_mov_b64 s[66:67], -1
	s_cbranch_vccnz .LBB0_705
	s_andn2_b64 vcc, exec, s[62:63]
	s_cbranch_vccnz .LBB0_702
	s_mov_b32 s34, s40
	s_mov_b32 s35, s40
	v_pk_mul_f32 v[134:135], v[38:39], s[34:35]
	v_pk_mul_f32 v[136:137], v[36:37], s[40:41]
	s_mov_b64 s[66:67], 0

; __device__ __forceinline__ u32x2 pack4(f32x4 v) { u32x2 r; r[0] = cvt_pk(v[0], v[1]); r[1] = cvt_pk(v[2], v[3]); return r; }
; __device__ __forceinline__ float sigmoidf_(float x) { return __builtin_amdgcn_rcpf(1.0f + __expf(-x)); }
; __device__ __forceinline__ float gelu_tanh(float x) { const float z = 1.5957691216057308f * (x + 0.044715f * x * x * x); return x * sigmoidf_(z); }
; __device__ __forceinline__ float siluf_(float x) { return x * sigmoidf_(x); }
; __device__ __forceinline__ void epilogue(const Params& p, const Unit& u, const f32x4 (&acc)[2][2][4][2], int wr, int wc, int fr, int fq) {
;     ...
; #pragma unroll
;     for (int ai = 0; ai < 2; ++ai)
; #pragma unroll
;       for (int m = 0; m < 4; ++m) {
;         bf16_t* rp = dst + (size_t)(row0 + ai * 128 + m * 16) * ld + cb + ct0;
; #pragma unroll
;         for (int bj = 0; bj < 2; ++bj)
; #pragma unroll
;           for (int n = 0; n < 2; ++n) {
;             f32x4 v = acc[ai][bj][m][n];
;             if (act == 1) { v[0] = sigmoidf_(v[0]); v[1] = sigmoidf_(v[1]); v[2] = sigmoidf_(v[2]); v[3] = sigmoidf_(v[3]); }
;             else if (act == 2) { v[0] = gelu_tanh(v[0]); v[1] = gelu_tanh(v[1]); v[2] = gelu_tanh(v[2]); v[3] = gelu_tanh(v[3]); }
;             else if (act == 3) { v[0] = siluf_(v[0]); v[1] = siluf_(v[1]); v[2] = siluf_(v[2]); v[3] = siluf_(v[3]); }
;             else { v = v * scale; }
;             *(u32x2*)(rp + bj * 128 + n * 16) = pack4(v);
;           }
.LBB0_709:
	v_add_u32_e32 v64, 0xb0, v66
	v_mad_i64_i32 v[66:67], s[34:35], s64, v64, 0
	v_lshl_add_u64 v[66:67], v[66:67], 1, v[132:133]
	v_cvt_pk_bf16_f32 v132, v136, v137
	v_cvt_pk_bf16_f32 v133, v134, v135
	s_and_b64 vcc, exec, s[38:39]
	ds_bpermute_b32 v132, v140, v132
	ds_bpermute_b32 v133, v140, v133
	s_waitcnt lgkmcnt(0)
	global_store_dwordx2 v[66:67], v[132:133], off
	s_cbranch_vccnz .LBB0_771
	s_and_b64 vcc, exec, s[36:37]
	s_mov_b64 s[64:65], -1
	s_cbranch_vccnz .LBB0_716
	s_andn2_b64 vcc, exec, s[62:63]
	s_cbranch_vccnz .LBB0_713
	s_mov_b32 s34, s40
	s_mov_b32 s35, s40
	v_pk_mul_f32 v[132:133], v[34:35], s[34:35]
	v_pk_mul_f32 v[134:135], v[32:33], s[40:41]
	s_mov_b64 s[64:65], 0

; __device__ __forceinline__ u32x2 pack4(f32x4 v) { u32x2 r; r[0] = cvt_pk(v[0], v[1]); r[1] = cvt_pk(v[2], v[3]); return r; }
; __device__ __forceinline__ float sigmoidf_(float x) { return __builtin_amdgcn_rcpf(1.0f + __expf(-x)); }
; __device__ __forceinline__ float gelu_tanh(float x) { const float z = 1.5957691216057308f * (x + 0.044715f * x * x * x); return x * sigmoidf_(z); }
; __device__ __forceinline__ float siluf_(float x) { return x * sigmoidf_(x); }
; __device__ __forceinline__ void epilogue(const Params& p, const Unit& u, const f32x4 (&acc)[2][2][4][2], int wr, int wc, int fr, int fq) {
;     ...
; #pragma unroll
;     for (int ai = 0; ai < 2; ++ai)
; #pragma unroll
;       for (int m = 0; m < 4; ++m) {
;         bf16_t* rp = dst + (size_t)(row0 + ai * 128 + m * 16) * ld + cb + ct0;
; #pragma unroll
;         for (int bj = 0; bj < 2; ++bj)
; #pragma unroll
;           for (int n = 0; n < 2; ++n) {
;             f32x4 v = acc[ai][bj][m][n];
;             if (act == 1) { v[0] = sigmoidf_(v[0]); v[1] = sigmoidf_(v[1]); v[2] = sigmoidf_(v[2]); v[3] = sigmoidf_(v[3]); }
;             else if (act == 2) { v[0] = gelu_tanh(v[0]); v[1] = gelu_tanh(v[1]); v[2] = gelu_tanh(v[2]); v[3] = gelu_tanh(v[3]); }
;             else if (act == 3) { v[0] = siluf_(v[0]); v[1] = siluf_(v[1]); v[2] = siluf_(v[2]); v[3] = siluf_(v[3]); }
;             else { v = v * scale; }
;             *(u32x2*)(rp + bj * 128 + n * 16) = pack4(v);
;           }
.LBB0_720:
	v_cvt_pk_bf16_f32 v134, v134, v135
	v_cvt_pk_bf16_f32 v135, v132, v133
	s_and_b64 vcc, exec, s[38:39]
	ds_bpermute_b32 v134, v140, v134
	ds_bpermute_b32 v135, v140, v135
	s_waitcnt lgkmcnt(0)
	global_store_dwordx2 v[66:67], v[134:135], off offset:32
	s_cbranch_vccnz .LBB0_772
	s_and_b64 vcc, exec, s[36:37]
	s_mov_b64 s[64:65], -1
	s_cbranch_vccnz .LBB0_727
	s_andn2_b64 vcc, exec, s[62:63]
	s_cbranch_vccnz .LBB0_724
	s_mov_b32 s34, s40
	s_mov_b32 s35, s40
	v_pk_mul_f32 v[132:133], v[6:7], s[34:35]
	v_pk_mul_f32 v[134:135], v[4:5], s[40:41]
	s_mov_b64 s[64:65], 0

; __device__ __forceinline__ u32x2 pack4(f32x4 v) { u32x2 r; r[0] = cvt_pk(v[0], v[1]); r[1] = cvt_pk(v[2], v[3]); return r; }
; __device__ __forceinline__ float sigmoidf_(float x) { return __builtin_amdgcn_rcpf(1.0f + __expf(-x)); }
; __device__ __forceinline__ float gelu_tanh(float x) { const float z = 1.5957691216057308f * (x + 0.044715f * x * x * x); return x * sigmoidf_(z); }
; __device__ __forceinline__ float siluf_(float x) { return x * sigmoidf_(x); }
; __device__ __forceinline__ void epilogue(const Params& p, const Unit& u, const f32x4 (&acc)[2][2][4][2], int wr, int wc, int fr, int fq) {
;     ...
; #pragma unroll
;     for (int ai = 0; ai < 2; ++ai)
; #pragma unroll
;       for (int m = 0; m < 4; ++m) {
;         bf16_t* rp = dst + (size_t)(row0 + ai * 128 + m * 16) * ld + cb + ct0;
; #pragma unroll
;         for (int bj = 0; bj < 2; ++bj)
; #pragma unroll
;           for (int n = 0; n < 2; ++n) {
;             f32x4 v = acc[ai][bj][m][n];
;             if (act == 1) { v[0] = sigmoidf_(v[0]); v[1] = sigmoidf_(v[1]); v[2] = sigmoidf_(v[2]); v[3] = sigmoidf_(v[3]); }
;             else if (act == 2) { v[0] = gelu_tanh(v[0]); v[1] = gelu_tanh(v[1]); v[2] = gelu_tanh(v[2]); v[3] = gelu_tanh(v[3]); }
;             else if (act == 3) { v[0] = siluf_(v[0]); v[1] = siluf_(v[1]); v[2] = siluf_(v[2]); v[3] = siluf_(v[3]); }
;             else { v = v * scale; }
;             *(u32x2*)(rp + bj * 128 + n * 16) = pack4(v);
;           }
.LBB0_731:
	v_cvt_pk_bf16_f32 v134, v134, v135
	v_cvt_pk_bf16_f32 v135, v132, v133
	s_and_b64 vcc, exec, s[38:39]
	ds_bpermute_b32 v134, v140, v134
	ds_bpermute_b32 v135, v140, v135
	s_waitcnt lgkmcnt(0)
	global_store_dwordx2 v[66:67], v[134:135], off offset:256
	s_cbranch_vccnz .LBB0_773
	s_and_b64 vcc, exec, s[36:37]
	s_mov_b64 s[36:37], -1
	s_cbranch_vccnz .LBB0_738
	s_andn2_b64 vcc, exec, s[62:63]
	s_cbranch_vccnz .LBB0_735
	s_mov_b32 s34, s40
	s_mov_b32 s35, s40
	v_pk_mul_f32 v[132:133], v[2:3], s[34:35]
	v_pk_mul_f32 v[134:135], v[0:1], s[40:41]
	s_mov_b64 s[36:37], 0

; __device__ __forceinline__ u32x2 pack4(f32x4 v) { u32x2 r; r[0] = cvt_pk(v[0], v[1]); r[1] = cvt_pk(v[2], v[3]); return r; }
; __device__ __forceinline__ float sigmoidf_(float x) { return __builtin_amdgcn_rcpf(1.0f + __expf(-x)); }
; __device__ __forceinline__ float gelu_tanh(float x) { const float z = 1.5957691216057308f * (x + 0.044715f * x * x * x); return x * sigmoidf_(z); }
; __device__ __forceinline__ float siluf_(float x) { return x * sigmoidf_(x); }
; __device__ __forceinline__ void epilogue(const Params& p, const Unit& u, const f32x4 (&acc)[2][2][4][2], int wr, int wc, int fr, int fq) {
;     ...
; #pragma unroll
;     for (int ai = 0; ai < 2; ++ai)
; #pragma unroll
;       for (int m = 0; m < 4; ++m) {
;         bf16_t* rp = dst + (size_t)(row0 + ai * 128 + m * 16) * ld + cb + ct0;
; #pragma unroll
;         for (int bj = 0; bj < 2; ++bj)
; #pragma unroll
;           for (int n = 0; n < 2; ++n) {
;             f32x4 v = acc[ai][bj][m][n];
;             if (act == 1) { v[0] = sigmoidf_(v[0]); v[1] = sigmoidf_(v[1]); v[2] = sigmoidf_(v[2]); v[3] = sigmoidf_(v[3]); }
;             else if (act == 2) { v[0] = gelu_tanh(v[0]); v[1] = gelu_tanh(v[1]); v[2] = gelu_tanh(v[2]); v[3] = gelu_tanh(v[3]); }
;             else if (act == 3) { v[0] = siluf_(v[0]); v[1] = siluf_(v[1]); v[2] = siluf_(v[2]); v[3] = siluf_(v[3]); }
;             else { v = v * scale; }
;             *(u32x2*)(rp + bj * 128 + n * 16) = pack4(v);
;           }
.LBB0_742:
	v_cvt_pk_bf16_f32 v134, v134, v135
	v_cvt_pk_bf16_f32 v135, v132, v133
	ds_bpermute_b32 v134, v140, v134
	ds_bpermute_b32 v135, v140, v135
	s_waitcnt lgkmcnt(0)
	global_store_dwordx2 v[66:67], v[134:135], off offset:288
	s_andn2_b64 vcc, exec, s[58:59]
	s_cbranch_vccnz .LBB0_294
	s_branch .LBB0_988
